# final RMSNorm: read-once bf16 residual-row loads marked nt (gamma loads keep default policy)
# speedup vs baseline: 1.0035x; 1.0035x over previous
.LBB0_969:
	s_waitcnt vmcnt(24)
	v_lshl_add_u64 v[20:21], s[84:85], 0, v[8:9]
	global_load_dwordx4 v[16:19], v[2:3], off
	global_load_dword v30, v[20:21], off
	s_waitcnt vmcnt(25)
	v_lshl_add_u64 v[22:23], s[84:85], 0, v[10:11]
	s_waitcnt vmcnt(24)
	v_add_co_u32_e32 v28, vcc, 0x4000000, v22
	v_add_u32_e32 v14, s2, v14
	s_nop 0
	v_addc_co_u32_e32 v29, vcc, 0, v23, vcc
	global_load_dwordx4 v[20:23], v[28:29], off nt
	global_load_dwordx4 v[24:27], v[2:3], off offset:16
	v_lshl_add_u64 v[8:9], v[8:9], 0, s[4:5]
	v_lshl_add_u64 v[10:11], v[10:11], 0, s[6:7]
	s_waitcnt vmcnt(2)
	v_fmamk_f32 v30, v30, 0x3a000000, v15
	v_mul_f32_e32 v31, 0x4b800000, v30
	v_cmp_gt_f32_e32 vcc, s3, v30
	s_waitcnt vmcnt(1)
	v_lshlrev_b32_e32 v32, 16, v22
	v_cndmask_b32_e32 v34, v30, v31, vcc
	v_rsq_f32_e32 v34, v34
	v_lshlrev_b32_e32 v30, 16, v20
	v_and_b32_e32 v31, 0xffff0000, v20
	v_lshlrev_b32_e32 v20, 16, v21
	v_mul_f32_e32 v35, 0x45800000, v34
	v_and_b32_e32 v21, 0xffff0000, v21
	v_cndmask_b32_e32 v34, v34, v35, vcc
	v_and_b32_e32 v33, 0xffff0000, v22
	v_lshlrev_b32_e32 v22, 16, v23
	v_and_b32_e32 v23, 0xffff0000, v23
	v_pk_mul_f32 v[30:31], v[34:35], v[30:31] op_sel_hi:[0,1]
	v_pk_mul_f32 v[20:21], v[34:35], v[20:21] op_sel_hi:[0,1]
	v_pk_mul_f32 v[32:33], v[34:35], v[32:33] op_sel_hi:[0,1]
	v_pk_mul_f32 v[22:23], v[34:35], v[22:23] op_sel_hi:[0,1]
	v_pk_mul_f32 v[18:19], v[18:19], v[20:21]
	v_pk_mul_f32 v[16:17], v[16:17], v[30:31]
	s_waitcnt vmcnt(0)
	v_pk_mul_f32 v[22:23], v[26:27], v[22:23]
	v_pk_mul_f32 v[20:21], v[24:25], v[32:33]
	global_store_dwordx4 v[12:13], v[16:19], off offset:-4096 nt
	global_store_dwordx4 v[12:13], v[20:23], off offset:-4080 nt
	global_load_dwordx4 v[16:19], v[28:29], off offset:1024 nt
	s_nop 0
	global_load_dwordx4 v[20:23], v[2:3], off offset:2048
	global_load_dwordx4 v[24:27], v[2:3], off offset:2064
	v_cmp_lt_i32_e32 vcc, s12, v14
	s_or_b64 s[10:11], vcc, s[10:11]
	s_waitcnt vmcnt(2)
	v_lshlrev_b32_e32 v30, 16, v16
	v_and_b32_e32 v31, 0xffff0000, v16
	v_lshlrev_b32_e32 v16, 16, v17
	v_and_b32_e32 v17, 0xffff0000, v17
	v_lshlrev_b32_e32 v32, 16, v18
	v_and_b32_e32 v33, 0xffff0000, v18
	v_lshlrev_b32_e32 v18, 16, v19
	v_and_b32_e32 v19, 0xffff0000, v19
	v_pk_mul_f32 v[30:31], v[34:35], v[30:31] op_sel_hi:[0,1]
	v_pk_mul_f32 v[16:17], v[34:35], v[16:17] op_sel_hi:[0,1]
	v_pk_mul_f32 v[32:33], v[34:35], v[32:33] op_sel_hi:[0,1]
	v_pk_mul_f32 v[36:37], v[34:35], v[18:19] op_sel_hi:[0,1]
	s_waitcnt vmcnt(1)
	v_pk_mul_f32 v[18:19], v[22:23], v[16:17]
	v_pk_mul_f32 v[16:17], v[20:21], v[30:31]
	s_waitcnt vmcnt(0)
	v_pk_mul_f32 v[22:23], v[26:27], v[36:37]
	v_pk_mul_f32 v[20:21], v[24:25], v[32:33]
	global_store_dwordx4 v[12:13], v[16:19], off offset:-2048 nt
	global_store_dwordx4 v[12:13], v[20:23], off offset:-2032 nt
	global_load_dwordx4 v[16:19], v[28:29], off offset:2048 nt
	s_nop 0
	global_load_dwordx4 v[20:23], v[4:5], off
	global_load_dwordx4 v[24:27], v[4:5], off offset:16
	s_waitcnt vmcnt(2)
	v_lshlrev_b32_e32 v30, 16, v16
	v_and_b32_e32 v31, 0xffff0000, v16
	v_lshlrev_b32_e32 v16, 16, v17
	v_and_b32_e32 v17, 0xffff0000, v17
	v_lshlrev_b32_e32 v32, 16, v18
	v_and_b32_e32 v33, 0xffff0000, v18
	v_lshlrev_b32_e32 v18, 16, v19
	v_and_b32_e32 v19, 0xffff0000, v19
	v_pk_mul_f32 v[30:31], v[34:35], v[30:31] op_sel_hi:[0,1]
	v_pk_mul_f32 v[16:17], v[34:35], v[16:17] op_sel_hi:[0,1]
	v_pk_mul_f32 v[32:33], v[34:35], v[32:33] op_sel_hi:[0,1]
	v_pk_mul_f32 v[36:37], v[34:35], v[18:19] op_sel_hi:[0,1]
	s_waitcnt vmcnt(1)
	v_pk_mul_f32 v[18:19], v[22:23], v[16:17]
	v_pk_mul_f32 v[16:17], v[20:21], v[30:31]
	s_waitcnt vmcnt(0)
	v_pk_mul_f32 v[22:23], v[26:27], v[36:37]
	v_pk_mul_f32 v[20:21], v[24:25], v[32:33]
	global_store_dwordx4 v[12:13], v[16:19], off nt
	global_store_dwordx4 v[12:13], v[20:23], off offset:16 nt
	global_load_dwordx4 v[16:19], v[28:29], off offset:3072 nt
	s_nop 0
	global_load_dwordx4 v[20:23], v[6:7], off
	global_load_dwordx4 v[24:27], v[6:7], off offset:16
	s_waitcnt vmcnt(2)
	v_lshlrev_b32_e32 v28, 16, v16
	v_and_b32_e32 v29, 0xffff0000, v16
	v_lshlrev_b32_e32 v16, 16, v17
	v_and_b32_e32 v17, 0xffff0000, v17
	v_lshlrev_b32_e32 v30, 16, v18
	v_and_b32_e32 v31, 0xffff0000, v18
	v_lshlrev_b32_e32 v18, 16, v19
	v_and_b32_e32 v19, 0xffff0000, v19
	v_pk_mul_f32 v[28:29], v[34:35], v[28:29] op_sel_hi:[0,1]
	v_pk_mul_f32 v[16:17], v[34:35], v[16:17] op_sel_hi:[0,1]
	v_pk_mul_f32 v[30:31], v[34:35], v[30:31] op_sel_hi:[0,1]
	v_pk_mul_f32 v[32:33], v[34:35], v[18:19] op_sel_hi:[0,1]
	s_waitcnt vmcnt(1)
	v_pk_mul_f32 v[18:19], v[22:23], v[16:17]
	v_pk_mul_f32 v[16:17], v[20:21], v[28:29]
	s_waitcnt vmcnt(0)
	v_pk_mul_f32 v[22:23], v[26:27], v[32:33]
	v_pk_mul_f32 v[20:21], v[24:25], v[30:31]
	global_store_dwordx4 v[12:13], v[16:19], off offset:2048 nt
	global_store_dwordx4 v[12:13], v[20:23], off offset:2064 nt
	v_lshl_add_u64 v[12:13], v[12:13], 0, s[8:9]
	s_andn2_b64 exec, exec, s[10:11]
	s_cbranch_execnz .LBB0_969
